# code placement: the 11 GEMM K-loop heads aligned to 64 bytes
# baseline (speedup 1.0000x reference)
.LBB0_154:
	s_ashr_i32 s15, s14, 31
	v_cmp_lt_i64_e32 vcc, s[16:17], v[142:143]
	s_lshl_b64 s[16:17], s[14:15], 19
	s_add_u32 s16, s44, s16
	s_addc_u32 s17, s45, s17
	s_and_b64 s[18:19], vcc, exec
	s_cselect_b32 s15, s17, s21
	s_cselect_b32 s82, s16, s20
	s_ashr_i32 s13, s12, 31
	s_lshl_b64 s[18:19], s[12:13], 19
	s_add_u32 s18, s60, s18
	s_addc_u32 s19, s61, s19
	s_and_b64 s[28:29], vcc, exec
	s_cselect_b32 s13, s19, s27
	s_cselect_b32 s83, s18, s26
	s_add_u32 s20, s20, 0x40080
	s_addc_u32 s21, s21, 0
	s_add_u32 s84, s26, 0x100
	v_mov_b32_e32 v0, 0
	s_addc_u32 s85, s27, 0
	s_mov_b32 s86, -2
	v_mov_b32_e32 v1, v0
	v_mov_b32_e32 v2, v0
	v_mov_b32_e32 v3, v0
	v_mov_b32_e32 v4, v0
	v_mov_b32_e32 v5, v0
	v_mov_b32_e32 v6, v0
	v_mov_b32_e32 v7, v0
	v_mov_b32_e32 v8, v0
	v_mov_b32_e32 v9, v0
	v_mov_b32_e32 v10, v0
	v_mov_b32_e32 v11, v0
	v_mov_b32_e32 v12, v0
	v_mov_b32_e32 v13, v0
	v_mov_b32_e32 v14, v0
	v_mov_b32_e32 v15, v0
	v_mov_b32_e32 v24, v0
	v_mov_b32_e32 v25, v0
	v_mov_b32_e32 v26, v0
	v_mov_b32_e32 v27, v0
	v_mov_b32_e32 v28, v0
	v_mov_b32_e32 v29, v0
	v_mov_b32_e32 v30, v0
	v_mov_b32_e32 v31, v0
	v_mov_b32_e32 v40, v0
	v_mov_b32_e32 v41, v0
	v_mov_b32_e32 v42, v0
	v_mov_b32_e32 v43, v0
	v_mov_b32_e32 v44, v0
	v_mov_b32_e32 v45, v0
	v_mov_b32_e32 v46, v0
	v_mov_b32_e32 v47, v0
	v_mov_b32_e32 v16, v0
	v_mov_b32_e32 v17, v0
	v_mov_b32_e32 v18, v0
	v_mov_b32_e32 v19, v0
	v_mov_b32_e32 v20, v0
	v_mov_b32_e32 v21, v0
	v_mov_b32_e32 v22, v0
	v_mov_b32_e32 v23, v0
	v_mov_b32_e32 v32, v0
	v_mov_b32_e32 v33, v0
	v_mov_b32_e32 v34, v0
	v_mov_b32_e32 v35, v0
	v_mov_b32_e32 v36, v0
	v_mov_b32_e32 v37, v0
	v_mov_b32_e32 v38, v0
	v_mov_b32_e32 v39, v0
	v_mov_b32_e32 v48, v0
	v_mov_b32_e32 v49, v0
	v_mov_b32_e32 v50, v0
	v_mov_b32_e32 v51, v0
	v_mov_b32_e32 v52, v0
	v_mov_b32_e32 v53, v0
	v_mov_b32_e32 v54, v0
	v_mov_b32_e32 v55, v0
	v_mov_b32_e32 v56, v0
	v_mov_b32_e32 v57, v0
	v_mov_b32_e32 v58, v0
	v_mov_b32_e32 v59, v0
	v_mov_b32_e32 v60, v0
	v_mov_b32_e32 v61, v0
	v_mov_b32_e32 v62, v0
	v_mov_b32_e32 v63, v0
	v_mov_b32_e32 v64, v0
	v_mov_b32_e32 v65, v0
	v_mov_b32_e32 v66, v0
	v_mov_b32_e32 v67, v0
	v_mov_b32_e32 v68, v0
	v_mov_b32_e32 v69, v0
	v_mov_b32_e32 v70, v0
	v_mov_b32_e32 v71, v0
	v_mov_b32_e32 v72, v0
	v_mov_b32_e32 v73, v0
	v_mov_b32_e32 v74, v0
	v_mov_b32_e32 v75, v0
	v_mov_b32_e32 v76, v0
	v_mov_b32_e32 v77, v0
	v_mov_b32_e32 v78, v0
	v_mov_b32_e32 v79, v0
	v_mov_b32_e32 v88, v0
	v_mov_b32_e32 v89, v0
	v_mov_b32_e32 v90, v0
	v_mov_b32_e32 v91, v0
	v_mov_b32_e32 v92, v0
	v_mov_b32_e32 v93, v0
	v_mov_b32_e32 v94, v0
	v_mov_b32_e32 v95, v0
	v_mov_b32_e32 v104, v0
	v_mov_b32_e32 v105, v0
	v_mov_b32_e32 v106, v0
	v_mov_b32_e32 v107, v0
	v_mov_b32_e32 v108, v0
	v_mov_b32_e32 v109, v0
	v_mov_b32_e32 v110, v0
	v_mov_b32_e32 v111, v0
	v_mov_b32_e32 v80, v0
	v_mov_b32_e32 v81, v0
	v_mov_b32_e32 v82, v0
	v_mov_b32_e32 v83, v0
	v_mov_b32_e32 v84, v0
	v_mov_b32_e32 v85, v0
	v_mov_b32_e32 v86, v0
	v_mov_b32_e32 v87, v0
	v_mov_b32_e32 v96, v0
	v_mov_b32_e32 v97, v0
	v_mov_b32_e32 v98, v0
	v_mov_b32_e32 v99, v0
	v_mov_b32_e32 v100, v0
	v_mov_b32_e32 v101, v0
	v_mov_b32_e32 v102, v0
	v_mov_b32_e32 v103, v0
	v_mov_b32_e32 v112, v0
	v_mov_b32_e32 v113, v0
	v_mov_b32_e32 v114, v0
	v_mov_b32_e32 v115, v0
	v_mov_b32_e32 v116, v0
	v_mov_b32_e32 v117, v0
	v_mov_b32_e32 v118, v0
	v_mov_b32_e32 v119, v0
	v_mov_b32_e32 v120, v0
	v_mov_b32_e32 v121, v0
	v_mov_b32_e32 v122, v0
	v_mov_b32_e32 v123, v0
	v_mov_b32_e32 v124, v0
	v_mov_b32_e32 v125, v0
	v_mov_b32_e32 v126, v0
	v_mov_b32_e32 v127, v0
	.p2align 6

.LBB0_485:
	s_ashr_i32 s19, s18, 31
	v_cmp_lt_i64_e32 vcc, s[20:21], v[142:143]
	s_lshl_b64 s[20:21], s[18:19], 19
	s_add_u32 s20, s44, s20
	s_addc_u32 s21, s45, s21
	s_and_b64 s[26:27], vcc, exec
	s_cselect_b32 s19, s21, s29
	s_cselect_b32 s80, s20, s28
	s_ashr_i32 s17, s16, 31
	s_lshl_b64 s[26:27], s[16:17], 19
	s_add_u32 s26, s62, s26
	s_addc_u32 s27, s63, s27
	s_and_b64 s[34:35], vcc, exec
	s_cselect_b32 s17, s27, s31
	s_cselect_b32 s81, s26, s30
	s_add_u32 s28, s28, 0x40080
	s_addc_u32 s29, s29, 0
	s_add_u32 s82, s30, 0x100
	v_mov_b32_e32 v0, 0
	s_addc_u32 s83, s31, 0
	s_mov_b32 s84, -2
	v_mov_b32_e32 v1, v0
	v_mov_b32_e32 v2, v0
	v_mov_b32_e32 v3, v0
	v_mov_b32_e32 v4, v0
	v_mov_b32_e32 v5, v0
	v_mov_b32_e32 v6, v0
	v_mov_b32_e32 v7, v0
	v_mov_b32_e32 v8, v0
	v_mov_b32_e32 v9, v0
	v_mov_b32_e32 v10, v0
	v_mov_b32_e32 v11, v0
	v_mov_b32_e32 v12, v0
	v_mov_b32_e32 v13, v0
	v_mov_b32_e32 v14, v0
	v_mov_b32_e32 v15, v0
	v_mov_b32_e32 v24, v0
	v_mov_b32_e32 v25, v0
	v_mov_b32_e32 v26, v0
	v_mov_b32_e32 v27, v0
	v_mov_b32_e32 v28, v0
	v_mov_b32_e32 v29, v0
	v_mov_b32_e32 v30, v0
	v_mov_b32_e32 v31, v0
	v_mov_b32_e32 v40, v0
	v_mov_b32_e32 v41, v0
	v_mov_b32_e32 v42, v0
	v_mov_b32_e32 v43, v0
	v_mov_b32_e32 v44, v0
	v_mov_b32_e32 v45, v0
	v_mov_b32_e32 v46, v0
	v_mov_b32_e32 v47, v0
	v_mov_b32_e32 v16, v0
	v_mov_b32_e32 v17, v0
	v_mov_b32_e32 v18, v0
	v_mov_b32_e32 v19, v0
	v_mov_b32_e32 v20, v0
	v_mov_b32_e32 v21, v0
	v_mov_b32_e32 v22, v0
	v_mov_b32_e32 v23, v0
	v_mov_b32_e32 v32, v0
	v_mov_b32_e32 v33, v0
	v_mov_b32_e32 v34, v0
	v_mov_b32_e32 v35, v0
	v_mov_b32_e32 v36, v0
	v_mov_b32_e32 v37, v0
	v_mov_b32_e32 v38, v0
	v_mov_b32_e32 v39, v0
	v_mov_b32_e32 v48, v0
	v_mov_b32_e32 v49, v0
	v_mov_b32_e32 v50, v0
	v_mov_b32_e32 v51, v0
	v_mov_b32_e32 v52, v0
	v_mov_b32_e32 v53, v0
	v_mov_b32_e32 v54, v0
	v_mov_b32_e32 v55, v0
	v_mov_b32_e32 v56, v0
	v_mov_b32_e32 v57, v0
	v_mov_b32_e32 v58, v0
	v_mov_b32_e32 v59, v0
	v_mov_b32_e32 v60, v0
	v_mov_b32_e32 v61, v0
	v_mov_b32_e32 v62, v0
	v_mov_b32_e32 v63, v0
	v_mov_b32_e32 v64, v0
	v_mov_b32_e32 v65, v0
	v_mov_b32_e32 v66, v0
	v_mov_b32_e32 v67, v0
	v_mov_b32_e32 v68, v0
	v_mov_b32_e32 v69, v0
	v_mov_b32_e32 v70, v0
	v_mov_b32_e32 v71, v0
	v_mov_b32_e32 v72, v0
	v_mov_b32_e32 v73, v0
	v_mov_b32_e32 v74, v0
	v_mov_b32_e32 v75, v0
	v_mov_b32_e32 v76, v0
	v_mov_b32_e32 v77, v0
	v_mov_b32_e32 v78, v0
	v_mov_b32_e32 v79, v0
	v_mov_b32_e32 v88, v0
	v_mov_b32_e32 v89, v0
	v_mov_b32_e32 v90, v0
	v_mov_b32_e32 v91, v0
	v_mov_b32_e32 v92, v0
	v_mov_b32_e32 v93, v0
	v_mov_b32_e32 v94, v0
	v_mov_b32_e32 v95, v0
	v_mov_b32_e32 v104, v0
	v_mov_b32_e32 v105, v0
	v_mov_b32_e32 v106, v0
	v_mov_b32_e32 v107, v0
	v_mov_b32_e32 v108, v0
	v_mov_b32_e32 v109, v0
	v_mov_b32_e32 v110, v0
	v_mov_b32_e32 v111, v0
	v_mov_b32_e32 v80, v0
	v_mov_b32_e32 v81, v0
	v_mov_b32_e32 v82, v0
	v_mov_b32_e32 v83, v0
	v_mov_b32_e32 v84, v0
	v_mov_b32_e32 v85, v0
	v_mov_b32_e32 v86, v0
	v_mov_b32_e32 v87, v0
	v_mov_b32_e32 v96, v0
	v_mov_b32_e32 v97, v0
	v_mov_b32_e32 v98, v0
	v_mov_b32_e32 v99, v0
	v_mov_b32_e32 v100, v0
	v_mov_b32_e32 v101, v0
	v_mov_b32_e32 v102, v0
	v_mov_b32_e32 v103, v0
	v_mov_b32_e32 v112, v0
	v_mov_b32_e32 v113, v0
	v_mov_b32_e32 v114, v0
	v_mov_b32_e32 v115, v0
	v_mov_b32_e32 v116, v0
	v_mov_b32_e32 v117, v0
	v_mov_b32_e32 v118, v0
	v_mov_b32_e32 v119, v0
	v_mov_b32_e32 v120, v0
	v_mov_b32_e32 v121, v0
	v_mov_b32_e32 v122, v0
	v_mov_b32_e32 v123, v0
	v_mov_b32_e32 v124, v0
	v_mov_b32_e32 v125, v0
	v_mov_b32_e32 v126, v0
	v_mov_b32_e32 v127, v0
	.p2align 6

.LBB0_682:
	s_ashr_i32 s19, s18, 31
	v_cmp_lt_i64_e32 vcc, s[20:21], v[142:143]
	s_lshl_b64 s[20:21], s[18:19], 19
	s_add_u32 s20, s44, s20
	s_addc_u32 s21, s45, s21
	s_and_b64 s[26:27], vcc, exec
	s_cselect_b32 s19, s21, s31
	s_cselect_b32 s81, s20, s30
	s_ashr_i32 s17, s16, 31
	s_lshl_b64 s[26:27], s[16:17], 19
	s_add_u32 s26, s64, s26
	s_addc_u32 s27, s65, s27
	s_and_b64 s[54:55], vcc, exec
	s_cselect_b32 s17, s27, s35
	s_cselect_b32 s82, s26, s34
	s_add_u32 s30, s30, 0x40080
	s_addc_u32 s31, s31, 0
	s_add_u32 s83, s34, 0x100
	v_mov_b32_e32 v0, 0
	s_addc_u32 s84, s35, 0
	s_mov_b32 s85, -2
	v_mov_b32_e32 v1, v0
	v_mov_b32_e32 v2, v0
	v_mov_b32_e32 v3, v0
	v_mov_b32_e32 v4, v0
	v_mov_b32_e32 v5, v0
	v_mov_b32_e32 v6, v0
	v_mov_b32_e32 v7, v0
	v_mov_b32_e32 v16, v0
	v_mov_b32_e32 v17, v0
	v_mov_b32_e32 v18, v0
	v_mov_b32_e32 v19, v0
	v_mov_b32_e32 v20, v0
	v_mov_b32_e32 v21, v0
	v_mov_b32_e32 v22, v0
	v_mov_b32_e32 v23, v0
	v_mov_b32_e32 v32, v0
	v_mov_b32_e32 v33, v0
	v_mov_b32_e32 v34, v0
	v_mov_b32_e32 v35, v0
	v_mov_b32_e32 v36, v0
	v_mov_b32_e32 v37, v0
	v_mov_b32_e32 v38, v0
	v_mov_b32_e32 v39, v0
	v_mov_b32_e32 v48, v0
	v_mov_b32_e32 v49, v0
	v_mov_b32_e32 v50, v0
	v_mov_b32_e32 v51, v0
	v_mov_b32_e32 v52, v0
	v_mov_b32_e32 v53, v0
	v_mov_b32_e32 v54, v0
	v_mov_b32_e32 v55, v0
	v_mov_b32_e32 v8, v0
	v_mov_b32_e32 v9, v0
	v_mov_b32_e32 v10, v0
	v_mov_b32_e32 v11, v0
	v_mov_b32_e32 v12, v0
	v_mov_b32_e32 v13, v0
	v_mov_b32_e32 v14, v0
	v_mov_b32_e32 v15, v0
	v_mov_b32_e32 v24, v0
	v_mov_b32_e32 v25, v0
	v_mov_b32_e32 v26, v0
	v_mov_b32_e32 v27, v0
	v_mov_b32_e32 v28, v0
	v_mov_b32_e32 v29, v0
	v_mov_b32_e32 v30, v0
	v_mov_b32_e32 v31, v0
	v_mov_b32_e32 v40, v0
	v_mov_b32_e32 v41, v0
	v_mov_b32_e32 v42, v0
	v_mov_b32_e32 v43, v0
	v_mov_b32_e32 v44, v0
	v_mov_b32_e32 v45, v0
	v_mov_b32_e32 v46, v0
	v_mov_b32_e32 v47, v0
	v_mov_b32_e32 v56, v0
	v_mov_b32_e32 v57, v0
	v_mov_b32_e32 v58, v0
	v_mov_b32_e32 v59, v0
	v_mov_b32_e32 v60, v0
	v_mov_b32_e32 v61, v0
	v_mov_b32_e32 v62, v0
	v_mov_b32_e32 v63, v0
	v_mov_b32_e32 v64, v0
	v_mov_b32_e32 v65, v0
	v_mov_b32_e32 v66, v0
	v_mov_b32_e32 v67, v0
	v_mov_b32_e32 v68, v0
	v_mov_b32_e32 v69, v0
	v_mov_b32_e32 v70, v0
	v_mov_b32_e32 v71, v0
	v_mov_b32_e32 v80, v0
	v_mov_b32_e32 v81, v0
	v_mov_b32_e32 v82, v0
	v_mov_b32_e32 v83, v0
	v_mov_b32_e32 v84, v0
	v_mov_b32_e32 v85, v0
	v_mov_b32_e32 v86, v0
	v_mov_b32_e32 v87, v0
	v_mov_b32_e32 v96, v0
	v_mov_b32_e32 v97, v0
	v_mov_b32_e32 v98, v0
	v_mov_b32_e32 v99, v0
	v_mov_b32_e32 v100, v0
	v_mov_b32_e32 v101, v0
	v_mov_b32_e32 v102, v0
	v_mov_b32_e32 v103, v0
	v_mov_b32_e32 v112, v0
	v_mov_b32_e32 v113, v0
	v_mov_b32_e32 v114, v0
	v_mov_b32_e32 v115, v0
	v_mov_b32_e32 v116, v0
	v_mov_b32_e32 v117, v0
	v_mov_b32_e32 v118, v0
	v_mov_b32_e32 v119, v0
	v_mov_b32_e32 v72, v0
	v_mov_b32_e32 v73, v0
	v_mov_b32_e32 v74, v0
	v_mov_b32_e32 v75, v0
	v_mov_b32_e32 v76, v0
	v_mov_b32_e32 v77, v0
	v_mov_b32_e32 v78, v0
	v_mov_b32_e32 v79, v0
	v_mov_b32_e32 v88, v0
	v_mov_b32_e32 v89, v0
	v_mov_b32_e32 v90, v0
	v_mov_b32_e32 v91, v0
	v_mov_b32_e32 v92, v0
	v_mov_b32_e32 v93, v0
	v_mov_b32_e32 v94, v0
	v_mov_b32_e32 v95, v0
	v_mov_b32_e32 v104, v0
	v_mov_b32_e32 v105, v0
	v_mov_b32_e32 v106, v0
	v_mov_b32_e32 v107, v0
	v_mov_b32_e32 v108, v0
	v_mov_b32_e32 v109, v0
	v_mov_b32_e32 v110, v0
	v_mov_b32_e32 v111, v0
	v_mov_b32_e32 v120, v0
	v_mov_b32_e32 v121, v0
	v_mov_b32_e32 v122, v0
	v_mov_b32_e32 v123, v0
	v_mov_b32_e32 v124, v0
	v_mov_b32_e32 v125, v0
	v_mov_b32_e32 v126, v0
	v_mov_b32_e32 v127, v0
	.p2align 6

.LBB0_775:
	s_ashr_i32 s21, s20, 31
	v_cmp_lt_i64_e32 vcc, s[26:27], v[142:143]
	s_lshl_b64 s[26:27], s[20:21], 21
	s_add_u32 s26, s46, s26
	s_addc_u32 s27, s47, s27
	s_and_b64 s[28:29], vcc, exec
	s_cselect_b32 s21, s27, s31
	s_cselect_b32 s81, s26, s30
	s_ashr_i32 s19, s18, 31
	s_lshl_b64 s[28:29], s[18:19], 21
	s_add_u32 s28, s66, s28
	s_addc_u32 s29, s67, s29
	s_and_b64 s[54:55], vcc, exec
	s_cselect_b32 s19, s29, s35
	s_cselect_b32 s82, s28, s34
	s_add_u32 s30, s30, 0x100080
	s_addc_u32 s31, s31, 0
	s_add_u32 s83, s34, 0x100
	v_mov_b32_e32 v0, 0
	s_addc_u32 s84, s35, 0
	s_mov_b32 s85, -2
	v_mov_b32_e32 v1, v0
	v_mov_b32_e32 v2, v0
	v_mov_b32_e32 v3, v0
	v_mov_b32_e32 v4, v0
	v_mov_b32_e32 v5, v0
	v_mov_b32_e32 v6, v0
	v_mov_b32_e32 v7, v0
	v_mov_b32_e32 v8, v0
	v_mov_b32_e32 v9, v0
	v_mov_b32_e32 v10, v0
	v_mov_b32_e32 v11, v0
	v_mov_b32_e32 v12, v0
	v_mov_b32_e32 v13, v0
	v_mov_b32_e32 v14, v0
	v_mov_b32_e32 v15, v0
	v_mov_b32_e32 v24, v0
	v_mov_b32_e32 v25, v0
	v_mov_b32_e32 v26, v0
	v_mov_b32_e32 v27, v0
	v_mov_b32_e32 v28, v0
	v_mov_b32_e32 v29, v0
	v_mov_b32_e32 v30, v0
	v_mov_b32_e32 v31, v0
	v_mov_b32_e32 v40, v0
	v_mov_b32_e32 v41, v0
	v_mov_b32_e32 v42, v0
	v_mov_b32_e32 v43, v0
	v_mov_b32_e32 v44, v0
	v_mov_b32_e32 v45, v0
	v_mov_b32_e32 v46, v0
	v_mov_b32_e32 v47, v0
	v_mov_b32_e32 v16, v0
	v_mov_b32_e32 v17, v0
	v_mov_b32_e32 v18, v0
	v_mov_b32_e32 v19, v0
	v_mov_b32_e32 v20, v0
	v_mov_b32_e32 v21, v0
	v_mov_b32_e32 v22, v0
	v_mov_b32_e32 v23, v0
	v_mov_b32_e32 v32, v0
	v_mov_b32_e32 v33, v0
	v_mov_b32_e32 v34, v0
	v_mov_b32_e32 v35, v0
	v_mov_b32_e32 v36, v0
	v_mov_b32_e32 v37, v0
	v_mov_b32_e32 v38, v0
	v_mov_b32_e32 v39, v0
	v_mov_b32_e32 v48, v0
	v_mov_b32_e32 v49, v0
	v_mov_b32_e32 v50, v0
	v_mov_b32_e32 v51, v0
	v_mov_b32_e32 v52, v0
	v_mov_b32_e32 v53, v0
	v_mov_b32_e32 v54, v0
	v_mov_b32_e32 v55, v0
	v_mov_b32_e32 v56, v0
	v_mov_b32_e32 v57, v0
	v_mov_b32_e32 v58, v0
	v_mov_b32_e32 v59, v0
	v_mov_b32_e32 v60, v0
	v_mov_b32_e32 v61, v0
	v_mov_b32_e32 v62, v0
	v_mov_b32_e32 v63, v0
	v_mov_b32_e32 v64, v0
	v_mov_b32_e32 v65, v0
	v_mov_b32_e32 v66, v0
	v_mov_b32_e32 v67, v0
	v_mov_b32_e32 v68, v0
	v_mov_b32_e32 v69, v0
	v_mov_b32_e32 v70, v0
	v_mov_b32_e32 v71, v0
	v_mov_b32_e32 v72, v0
	v_mov_b32_e32 v73, v0
	v_mov_b32_e32 v74, v0
	v_mov_b32_e32 v75, v0
	v_mov_b32_e32 v76, v0
	v_mov_b32_e32 v77, v0
	v_mov_b32_e32 v78, v0
	v_mov_b32_e32 v79, v0
	v_mov_b32_e32 v88, v0
	v_mov_b32_e32 v89, v0
	v_mov_b32_e32 v90, v0
	v_mov_b32_e32 v91, v0
	v_mov_b32_e32 v92, v0
	v_mov_b32_e32 v93, v0
	v_mov_b32_e32 v94, v0
	v_mov_b32_e32 v95, v0
	v_mov_b32_e32 v104, v0
	v_mov_b32_e32 v105, v0
	v_mov_b32_e32 v106, v0
	v_mov_b32_e32 v107, v0
	v_mov_b32_e32 v108, v0
	v_mov_b32_e32 v109, v0
	v_mov_b32_e32 v110, v0
	v_mov_b32_e32 v111, v0
	v_mov_b32_e32 v80, v0
	v_mov_b32_e32 v81, v0
	v_mov_b32_e32 v82, v0
	v_mov_b32_e32 v83, v0
	v_mov_b32_e32 v84, v0
	v_mov_b32_e32 v85, v0
	v_mov_b32_e32 v86, v0
	v_mov_b32_e32 v87, v0
	v_mov_b32_e32 v96, v0
	v_mov_b32_e32 v97, v0
	v_mov_b32_e32 v98, v0
	v_mov_b32_e32 v99, v0
	v_mov_b32_e32 v100, v0
	v_mov_b32_e32 v101, v0
	v_mov_b32_e32 v102, v0
	v_mov_b32_e32 v103, v0
	v_mov_b32_e32 v112, v0
	v_mov_b32_e32 v113, v0
	v_mov_b32_e32 v114, v0
	v_mov_b32_e32 v115, v0
	v_mov_b32_e32 v116, v0
	v_mov_b32_e32 v117, v0
	v_mov_b32_e32 v118, v0
	v_mov_b32_e32 v119, v0
	v_mov_b32_e32 v120, v0
	v_mov_b32_e32 v121, v0
	v_mov_b32_e32 v122, v0
	v_mov_b32_e32 v123, v0
	v_mov_b32_e32 v124, v0
	v_mov_b32_e32 v125, v0
	v_mov_b32_e32 v126, v0
	v_mov_b32_e32 v127, v0
	.p2align 6

.LBB0_911:
	s_ashr_i32 s27, s26, 31
	v_cmp_lt_i64_e32 vcc, s[28:29], v[142:143]
	s_lshl_b64 s[28:29], s[26:27], 19
	s_add_u32 s28, s44, s28
	s_addc_u32 s29, s45, s29
	s_and_b64 s[30:31], vcc, exec
	s_cselect_b32 s27, s29, s35
	s_cselect_b32 s83, s28, s34
	s_ashr_i32 s21, s20, 31
	s_lshl_b64 s[30:31], s[20:21], 19
	s_add_u32 s30, s36, s30
	s_addc_u32 s31, s37, s31
	s_and_b64 s[56:57], vcc, exec
	s_cselect_b32 s21, s31, s55
	s_cselect_b32 s84, s30, s54
	s_add_u32 s34, s34, 0x40080
	s_addc_u32 s35, s35, 0
	s_add_u32 s85, s54, 0x100
	v_mov_b32_e32 v0, 0
	s_addc_u32 s86, s55, 0
	s_mov_b32 s87, -2
	v_mov_b32_e32 v1, v0
	v_mov_b32_e32 v2, v0
	v_mov_b32_e32 v3, v0
	v_mov_b32_e32 v4, v0
	v_mov_b32_e32 v5, v0
	v_mov_b32_e32 v6, v0
	v_mov_b32_e32 v7, v0
	v_mov_b32_e32 v8, v0
	v_mov_b32_e32 v9, v0
	v_mov_b32_e32 v10, v0
	v_mov_b32_e32 v11, v0
	v_mov_b32_e32 v12, v0
	v_mov_b32_e32 v13, v0
	v_mov_b32_e32 v14, v0
	v_mov_b32_e32 v15, v0
	v_mov_b32_e32 v24, v0
	v_mov_b32_e32 v25, v0
	v_mov_b32_e32 v26, v0
	v_mov_b32_e32 v27, v0
	v_mov_b32_e32 v28, v0
	v_mov_b32_e32 v29, v0
	v_mov_b32_e32 v30, v0
	v_mov_b32_e32 v31, v0
	v_mov_b32_e32 v40, v0
	v_mov_b32_e32 v41, v0
	v_mov_b32_e32 v42, v0
	v_mov_b32_e32 v43, v0
	v_mov_b32_e32 v44, v0
	v_mov_b32_e32 v45, v0
	v_mov_b32_e32 v46, v0
	v_mov_b32_e32 v47, v0
	v_mov_b32_e32 v16, v0
	v_mov_b32_e32 v17, v0
	v_mov_b32_e32 v18, v0
	v_mov_b32_e32 v19, v0
	v_mov_b32_e32 v20, v0
	v_mov_b32_e32 v21, v0
	v_mov_b32_e32 v22, v0
	v_mov_b32_e32 v23, v0
	v_mov_b32_e32 v32, v0
	v_mov_b32_e32 v33, v0
	v_mov_b32_e32 v34, v0
	v_mov_b32_e32 v35, v0
	v_mov_b32_e32 v36, v0
	v_mov_b32_e32 v37, v0
	v_mov_b32_e32 v38, v0
	v_mov_b32_e32 v39, v0
	v_mov_b32_e32 v48, v0
	v_mov_b32_e32 v49, v0
	v_mov_b32_e32 v50, v0
	v_mov_b32_e32 v51, v0
	v_mov_b32_e32 v52, v0
	v_mov_b32_e32 v53, v0
	v_mov_b32_e32 v54, v0
	v_mov_b32_e32 v55, v0
	v_mov_b32_e32 v56, v0
	v_mov_b32_e32 v57, v0
	v_mov_b32_e32 v58, v0
	v_mov_b32_e32 v59, v0
	v_mov_b32_e32 v60, v0
	v_mov_b32_e32 v61, v0
	v_mov_b32_e32 v62, v0
	v_mov_b32_e32 v63, v0
	v_mov_b32_e32 v64, v0
	v_mov_b32_e32 v65, v0
	v_mov_b32_e32 v66, v0
	v_mov_b32_e32 v67, v0
	v_mov_b32_e32 v68, v0
	v_mov_b32_e32 v69, v0
	v_mov_b32_e32 v70, v0
	v_mov_b32_e32 v71, v0
	v_mov_b32_e32 v72, v0
	v_mov_b32_e32 v73, v0
	v_mov_b32_e32 v74, v0
	v_mov_b32_e32 v75, v0
	v_mov_b32_e32 v76, v0
	v_mov_b32_e32 v77, v0
	v_mov_b32_e32 v78, v0
	v_mov_b32_e32 v79, v0
	v_mov_b32_e32 v88, v0
	v_mov_b32_e32 v89, v0
	v_mov_b32_e32 v90, v0
	v_mov_b32_e32 v91, v0
	v_mov_b32_e32 v92, v0
	v_mov_b32_e32 v93, v0
	v_mov_b32_e32 v94, v0
	v_mov_b32_e32 v95, v0
	v_mov_b32_e32 v104, v0
	v_mov_b32_e32 v105, v0
	v_mov_b32_e32 v106, v0
	v_mov_b32_e32 v107, v0
	v_mov_b32_e32 v108, v0
	v_mov_b32_e32 v109, v0
	v_mov_b32_e32 v110, v0
	v_mov_b32_e32 v111, v0
	v_mov_b32_e32 v80, v0
	v_mov_b32_e32 v81, v0
	v_mov_b32_e32 v82, v0
	v_mov_b32_e32 v83, v0
	v_mov_b32_e32 v84, v0
	v_mov_b32_e32 v85, v0
	v_mov_b32_e32 v86, v0
	v_mov_b32_e32 v87, v0
	v_mov_b32_e32 v96, v0
	v_mov_b32_e32 v97, v0
	v_mov_b32_e32 v98, v0
	v_mov_b32_e32 v99, v0
	v_mov_b32_e32 v100, v0
	v_mov_b32_e32 v101, v0
	v_mov_b32_e32 v102, v0
	v_mov_b32_e32 v103, v0
	v_mov_b32_e32 v112, v0
	v_mov_b32_e32 v113, v0
	v_mov_b32_e32 v114, v0
	v_mov_b32_e32 v115, v0
	v_mov_b32_e32 v116, v0
	v_mov_b32_e32 v117, v0
	v_mov_b32_e32 v118, v0
	v_mov_b32_e32 v119, v0
	v_mov_b32_e32 v120, v0
	v_mov_b32_e32 v121, v0
	v_mov_b32_e32 v122, v0
	v_mov_b32_e32 v123, v0
	v_mov_b32_e32 v124, v0
	v_mov_b32_e32 v125, v0
	v_mov_b32_e32 v126, v0
	v_mov_b32_e32 v127, v0
	.p2align 6

.LBB0_1115:
	s_ashr_i32 s19, s18, 31
	v_cmp_lt_i64_e32 vcc, s[20:21], v[138:139]
	s_lshl_b64 s[20:21], s[18:19], 19
	s_add_u32 s20, s44, s20
	s_addc_u32 s21, s45, s21
	s_and_b64 s[26:27], vcc, exec
	s_cselect_b32 s19, s21, s31
	s_cselect_b32 s73, s20, s30
	s_ashr_i32 s17, s16, 31
	s_lshl_b64 s[26:27], s[16:17], 19
	s_add_u32 s26, s38, s26
	s_addc_u32 s27, s39, s27
	s_and_b64 s[36:37], vcc, exec
	s_cselect_b32 s17, s27, s35
	s_cselect_b32 s74, s26, s34
	s_add_u32 s30, s30, 0x40080
	s_addc_u32 s31, s31, 0
	s_add_u32 s75, s34, 0x100
	v_mov_b32_e32 v4, 0
	s_addc_u32 s76, s35, 0
	s_mov_b32 s77, -2
	v_mov_b32_e32 v5, v4
	v_mov_b32_e32 v6, v4
	v_mov_b32_e32 v7, v4
	v_mov_b32_e32 v0, v4
	v_mov_b32_e32 v1, v4
	v_mov_b32_e32 v2, v4
	v_mov_b32_e32 v3, v4
	v_mov_b32_e32 v20, v4
	v_mov_b32_e32 v21, v4
	v_mov_b32_e32 v22, v4
	v_mov_b32_e32 v23, v4
	v_mov_b32_e32 v16, v4
	v_mov_b32_e32 v17, v4
	v_mov_b32_e32 v18, v4
	v_mov_b32_e32 v19, v4
	v_mov_b32_e32 v36, v4
	v_mov_b32_e32 v37, v4
	v_mov_b32_e32 v38, v4
	v_mov_b32_e32 v39, v4
	v_mov_b32_e32 v32, v4
	v_mov_b32_e32 v33, v4
	v_mov_b32_e32 v34, v4
	v_mov_b32_e32 v35, v4
	v_mov_b32_e32 v52, v4
	v_mov_b32_e32 v53, v4
	v_mov_b32_e32 v54, v4
	v_mov_b32_e32 v55, v4
	v_mov_b32_e32 v48, v4
	v_mov_b32_e32 v49, v4
	v_mov_b32_e32 v50, v4
	v_mov_b32_e32 v51, v4
	v_mov_b32_e32 v12, v4
	v_mov_b32_e32 v13, v4
	v_mov_b32_e32 v14, v4
	v_mov_b32_e32 v15, v4
	v_mov_b32_e32 v8, v4
	v_mov_b32_e32 v9, v4
	v_mov_b32_e32 v10, v4
	v_mov_b32_e32 v11, v4
	v_mov_b32_e32 v28, v4
	v_mov_b32_e32 v29, v4
	v_mov_b32_e32 v30, v4
	v_mov_b32_e32 v31, v4
	v_mov_b32_e32 v24, v4
	v_mov_b32_e32 v25, v4
	v_mov_b32_e32 v26, v4
	v_mov_b32_e32 v27, v4
	v_mov_b32_e32 v44, v4
	v_mov_b32_e32 v45, v4
	v_mov_b32_e32 v46, v4
	v_mov_b32_e32 v47, v4
	v_mov_b32_e32 v40, v4
	v_mov_b32_e32 v41, v4
	v_mov_b32_e32 v42, v4
	v_mov_b32_e32 v43, v4
	v_mov_b32_e32 v60, v4
	v_mov_b32_e32 v61, v4
	v_mov_b32_e32 v62, v4
	v_mov_b32_e32 v63, v4
	v_mov_b32_e32 v56, v4
	v_mov_b32_e32 v57, v4
	v_mov_b32_e32 v58, v4
	v_mov_b32_e32 v59, v4
	v_mov_b32_e32 v68, v4
	v_mov_b32_e32 v69, v4
	v_mov_b32_e32 v70, v4
	v_mov_b32_e32 v71, v4
	v_mov_b32_e32 v64, v4
	v_mov_b32_e32 v65, v4
	v_mov_b32_e32 v66, v4
	v_mov_b32_e32 v67, v4
	v_mov_b32_e32 v84, v4
	v_mov_b32_e32 v85, v4
	v_mov_b32_e32 v86, v4
	v_mov_b32_e32 v87, v4
	v_mov_b32_e32 v80, v4
	v_mov_b32_e32 v81, v4
	v_mov_b32_e32 v82, v4
	v_mov_b32_e32 v83, v4
	v_mov_b32_e32 v100, v4
	v_mov_b32_e32 v101, v4
	v_mov_b32_e32 v102, v4
	v_mov_b32_e32 v103, v4
	v_mov_b32_e32 v96, v4
	v_mov_b32_e32 v97, v4
	v_mov_b32_e32 v98, v4
	v_mov_b32_e32 v99, v4
	v_mov_b32_e32 v116, v4
	v_mov_b32_e32 v117, v4
	v_mov_b32_e32 v118, v4
	v_mov_b32_e32 v119, v4
	v_mov_b32_e32 v112, v4
	v_mov_b32_e32 v113, v4
	v_mov_b32_e32 v114, v4
	v_mov_b32_e32 v115, v4
	v_mov_b32_e32 v76, v4
	v_mov_b32_e32 v77, v4
	v_mov_b32_e32 v78, v4
	v_mov_b32_e32 v79, v4
	v_mov_b32_e32 v72, v4
	v_mov_b32_e32 v73, v4
	v_mov_b32_e32 v74, v4
	v_mov_b32_e32 v75, v4
	v_mov_b32_e32 v92, v4
	v_mov_b32_e32 v93, v4
	v_mov_b32_e32 v94, v4
	v_mov_b32_e32 v95, v4
	v_mov_b32_e32 v88, v4
	v_mov_b32_e32 v89, v4
	v_mov_b32_e32 v90, v4
	v_mov_b32_e32 v91, v4
	v_mov_b32_e32 v108, v4
	v_mov_b32_e32 v109, v4
	v_mov_b32_e32 v110, v4
	v_mov_b32_e32 v111, v4
	v_mov_b32_e32 v104, v4
	v_mov_b32_e32 v105, v4
	v_mov_b32_e32 v106, v4
	v_mov_b32_e32 v107, v4
	v_mov_b32_e32 v124, v4
	v_mov_b32_e32 v125, v4
	v_mov_b32_e32 v126, v4
	v_mov_b32_e32 v127, v4
	v_mov_b32_e32 v120, v4
	v_mov_b32_e32 v121, v4
	v_mov_b32_e32 v122, v4
	v_mov_b32_e32 v123, v4
	.p2align 6

.LBB0_1290:
	s_ashr_i32 s21, s20, 31
	v_cmp_lt_i64_e32 vcc, s[26:27], v[142:143]
	s_lshl_b64 s[26:27], s[20:21], 19
	s_add_u32 s26, s44, s26
	s_addc_u32 s27, s45, s27
	s_and_b64 s[28:29], vcc, exec
	s_cselect_b32 s21, s27, s35
	s_cselect_b32 s75, s26, s34
	s_ashr_i32 s19, s18, 31
	s_lshl_b64 s[28:29], s[18:19], 19
	s_add_u32 s28, s42, s28
	s_addc_u32 s29, s43, s29
	s_and_b64 s[38:39], vcc, exec
	s_cselect_b32 s19, s29, s37
	s_cselect_b32 s76, s28, s36
	s_add_u32 s34, s34, 0x40080
	s_addc_u32 s35, s35, 0
	s_add_u32 s77, s36, 0x100
	v_mov_b32_e32 v0, 0
	s_addc_u32 s78, s37, 0
	s_mov_b32 s79, -2
	v_mov_b32_e32 v1, v0
	v_mov_b32_e32 v2, v0
	v_mov_b32_e32 v3, v0
	v_mov_b32_e32 v4, v0
	v_mov_b32_e32 v5, v0
	v_mov_b32_e32 v6, v0
	v_mov_b32_e32 v7, v0
	v_mov_b32_e32 v16, v0
	v_mov_b32_e32 v17, v0
	v_mov_b32_e32 v18, v0
	v_mov_b32_e32 v19, v0
	v_mov_b32_e32 v20, v0
	v_mov_b32_e32 v21, v0
	v_mov_b32_e32 v22, v0
	v_mov_b32_e32 v23, v0
	v_mov_b32_e32 v32, v0
	v_mov_b32_e32 v33, v0
	v_mov_b32_e32 v34, v0
	v_mov_b32_e32 v35, v0
	v_mov_b32_e32 v36, v0
	v_mov_b32_e32 v37, v0
	v_mov_b32_e32 v38, v0
	v_mov_b32_e32 v39, v0
	v_mov_b32_e32 v48, v0
	v_mov_b32_e32 v49, v0
	v_mov_b32_e32 v50, v0
	v_mov_b32_e32 v51, v0
	v_mov_b32_e32 v52, v0
	v_mov_b32_e32 v53, v0
	v_mov_b32_e32 v54, v0
	v_mov_b32_e32 v55, v0
	v_mov_b32_e32 v8, v0
	v_mov_b32_e32 v9, v0
	v_mov_b32_e32 v10, v0
	v_mov_b32_e32 v11, v0
	v_mov_b32_e32 v12, v0
	v_mov_b32_e32 v13, v0
	v_mov_b32_e32 v14, v0
	v_mov_b32_e32 v15, v0
	v_mov_b32_e32 v24, v0
	v_mov_b32_e32 v25, v0
	v_mov_b32_e32 v26, v0
	v_mov_b32_e32 v27, v0
	v_mov_b32_e32 v28, v0
	v_mov_b32_e32 v29, v0
	v_mov_b32_e32 v30, v0
	v_mov_b32_e32 v31, v0
	v_mov_b32_e32 v40, v0
	v_mov_b32_e32 v41, v0
	v_mov_b32_e32 v42, v0
	v_mov_b32_e32 v43, v0
	v_mov_b32_e32 v44, v0
	v_mov_b32_e32 v45, v0
	v_mov_b32_e32 v46, v0
	v_mov_b32_e32 v47, v0
	v_mov_b32_e32 v56, v0
	v_mov_b32_e32 v57, v0
	v_mov_b32_e32 v58, v0
	v_mov_b32_e32 v59, v0
	v_mov_b32_e32 v60, v0
	v_mov_b32_e32 v61, v0
	v_mov_b32_e32 v62, v0
	v_mov_b32_e32 v63, v0
	v_mov_b32_e32 v64, v0
	v_mov_b32_e32 v65, v0
	v_mov_b32_e32 v66, v0
	v_mov_b32_e32 v67, v0
	v_mov_b32_e32 v68, v0
	v_mov_b32_e32 v69, v0
	v_mov_b32_e32 v70, v0
	v_mov_b32_e32 v71, v0
	v_mov_b32_e32 v80, v0
	v_mov_b32_e32 v81, v0
	v_mov_b32_e32 v82, v0
	v_mov_b32_e32 v83, v0
	v_mov_b32_e32 v84, v0
	v_mov_b32_e32 v85, v0
	v_mov_b32_e32 v86, v0
	v_mov_b32_e32 v87, v0
	v_mov_b32_e32 v96, v0
	v_mov_b32_e32 v97, v0
	v_mov_b32_e32 v98, v0
	v_mov_b32_e32 v99, v0
	v_mov_b32_e32 v100, v0
	v_mov_b32_e32 v101, v0
	v_mov_b32_e32 v102, v0
	v_mov_b32_e32 v103, v0
	v_mov_b32_e32 v112, v0
	v_mov_b32_e32 v113, v0
	v_mov_b32_e32 v114, v0
	v_mov_b32_e32 v115, v0
	v_mov_b32_e32 v116, v0
	v_mov_b32_e32 v117, v0
	v_mov_b32_e32 v118, v0
	v_mov_b32_e32 v119, v0
	v_mov_b32_e32 v72, v0
	v_mov_b32_e32 v73, v0
	v_mov_b32_e32 v74, v0
	v_mov_b32_e32 v75, v0
	v_mov_b32_e32 v76, v0
	v_mov_b32_e32 v77, v0
	v_mov_b32_e32 v78, v0
	v_mov_b32_e32 v79, v0
	v_mov_b32_e32 v88, v0
	v_mov_b32_e32 v89, v0
	v_mov_b32_e32 v90, v0
	v_mov_b32_e32 v91, v0
	v_mov_b32_e32 v92, v0
	v_mov_b32_e32 v93, v0
	v_mov_b32_e32 v94, v0
	v_mov_b32_e32 v95, v0
	v_mov_b32_e32 v104, v0
	v_mov_b32_e32 v105, v0
	v_mov_b32_e32 v106, v0
	v_mov_b32_e32 v107, v0
	v_mov_b32_e32 v108, v0
	v_mov_b32_e32 v109, v0
	v_mov_b32_e32 v110, v0
	v_mov_b32_e32 v111, v0
	v_mov_b32_e32 v120, v0
	v_mov_b32_e32 v121, v0
	v_mov_b32_e32 v122, v0
	v_mov_b32_e32 v123, v0
	v_mov_b32_e32 v124, v0
	v_mov_b32_e32 v125, v0
	v_mov_b32_e32 v126, v0
	v_mov_b32_e32 v127, v0
	.p2align 6

.LBB0_1309:
	s_ashr_i32 s27, s26, 31
	v_cmp_lt_i64_e32 vcc, s[28:29], v[142:143]
	s_lshl_b64 s[28:29], s[26:27], 19
	s_add_u32 s28, s44, s28
	s_addc_u32 s29, s45, s29
	s_and_b64 s[30:31], vcc, exec
	s_cselect_b32 s27, s29, s37
	s_cselect_b32 s73, s28, s36
	s_ashr_i32 s21, s20, 31
	s_lshl_b64 s[30:31], s[20:21], 19
	s_add_u32 s30, s8, s30
	s_addc_u32 s31, s9, s31
	s_and_b64 s[40:41], vcc, exec
	s_cselect_b32 s21, s31, s39
	s_cselect_b32 s74, s30, s38
	s_add_u32 s36, s36, 0x40080
	s_addc_u32 s37, s37, 0
	s_add_u32 s75, s38, 0x100
	v_mov_b32_e32 v0, 0
	s_addc_u32 s76, s39, 0
	s_mov_b32 s77, -2
	v_mov_b32_e32 v1, v0
	v_mov_b32_e32 v2, v0
	v_mov_b32_e32 v3, v0
	v_mov_b32_e32 v4, v0
	v_mov_b32_e32 v5, v0
	v_mov_b32_e32 v6, v0
	v_mov_b32_e32 v7, v0
	v_mov_b32_e32 v16, v0
	v_mov_b32_e32 v17, v0
	v_mov_b32_e32 v18, v0
	v_mov_b32_e32 v19, v0
	v_mov_b32_e32 v20, v0
	v_mov_b32_e32 v21, v0
	v_mov_b32_e32 v22, v0
	v_mov_b32_e32 v23, v0
	v_mov_b32_e32 v32, v0
	v_mov_b32_e32 v33, v0
	v_mov_b32_e32 v34, v0
	v_mov_b32_e32 v35, v0
	v_mov_b32_e32 v36, v0
	v_mov_b32_e32 v37, v0
	v_mov_b32_e32 v38, v0
	v_mov_b32_e32 v39, v0
	v_mov_b32_e32 v48, v0
	v_mov_b32_e32 v49, v0
	v_mov_b32_e32 v50, v0
	v_mov_b32_e32 v51, v0
	v_mov_b32_e32 v52, v0
	v_mov_b32_e32 v53, v0
	v_mov_b32_e32 v54, v0
	v_mov_b32_e32 v55, v0
	v_mov_b32_e32 v8, v0
	v_mov_b32_e32 v9, v0
	v_mov_b32_e32 v10, v0
	v_mov_b32_e32 v11, v0
	v_mov_b32_e32 v12, v0
	v_mov_b32_e32 v13, v0
	v_mov_b32_e32 v14, v0
	v_mov_b32_e32 v15, v0
	v_mov_b32_e32 v24, v0
	v_mov_b32_e32 v25, v0
	v_mov_b32_e32 v26, v0
	v_mov_b32_e32 v27, v0
	v_mov_b32_e32 v28, v0
	v_mov_b32_e32 v29, v0
	v_mov_b32_e32 v30, v0
	v_mov_b32_e32 v31, v0
	v_mov_b32_e32 v40, v0
	v_mov_b32_e32 v41, v0
	v_mov_b32_e32 v42, v0
	v_mov_b32_e32 v43, v0
	v_mov_b32_e32 v44, v0
	v_mov_b32_e32 v45, v0
	v_mov_b32_e32 v46, v0
	v_mov_b32_e32 v47, v0
	v_mov_b32_e32 v56, v0
	v_mov_b32_e32 v57, v0
	v_mov_b32_e32 v58, v0
	v_mov_b32_e32 v59, v0
	v_mov_b32_e32 v60, v0
	v_mov_b32_e32 v61, v0
	v_mov_b32_e32 v62, v0
	v_mov_b32_e32 v63, v0
	v_mov_b32_e32 v64, v0
	v_mov_b32_e32 v65, v0
	v_mov_b32_e32 v66, v0
	v_mov_b32_e32 v67, v0
	v_mov_b32_e32 v68, v0
	v_mov_b32_e32 v69, v0
	v_mov_b32_e32 v70, v0
	v_mov_b32_e32 v71, v0
	v_mov_b32_e32 v80, v0
	v_mov_b32_e32 v81, v0
	v_mov_b32_e32 v82, v0
	v_mov_b32_e32 v83, v0
	v_mov_b32_e32 v84, v0
	v_mov_b32_e32 v85, v0
	v_mov_b32_e32 v86, v0
	v_mov_b32_e32 v87, v0
	v_mov_b32_e32 v96, v0
	v_mov_b32_e32 v97, v0
	v_mov_b32_e32 v98, v0
	v_mov_b32_e32 v99, v0
	v_mov_b32_e32 v100, v0
	v_mov_b32_e32 v101, v0
	v_mov_b32_e32 v102, v0
	v_mov_b32_e32 v103, v0
	v_mov_b32_e32 v112, v0
	v_mov_b32_e32 v113, v0
	v_mov_b32_e32 v114, v0
	v_mov_b32_e32 v115, v0
	v_mov_b32_e32 v116, v0
	v_mov_b32_e32 v117, v0
	v_mov_b32_e32 v118, v0
	v_mov_b32_e32 v119, v0
	v_mov_b32_e32 v72, v0
	v_mov_b32_e32 v73, v0
	v_mov_b32_e32 v74, v0
	v_mov_b32_e32 v75, v0
	v_mov_b32_e32 v76, v0
	v_mov_b32_e32 v77, v0
	v_mov_b32_e32 v78, v0
	v_mov_b32_e32 v79, v0
	v_mov_b32_e32 v88, v0
	v_mov_b32_e32 v89, v0
	v_mov_b32_e32 v90, v0
	v_mov_b32_e32 v91, v0
	v_mov_b32_e32 v92, v0
	v_mov_b32_e32 v93, v0
	v_mov_b32_e32 v94, v0
	v_mov_b32_e32 v95, v0
	v_mov_b32_e32 v104, v0
	v_mov_b32_e32 v105, v0
	v_mov_b32_e32 v106, v0
	v_mov_b32_e32 v107, v0
	v_mov_b32_e32 v108, v0
	v_mov_b32_e32 v109, v0
	v_mov_b32_e32 v110, v0
	v_mov_b32_e32 v111, v0
	v_mov_b32_e32 v120, v0
	v_mov_b32_e32 v121, v0
	v_mov_b32_e32 v122, v0
	v_mov_b32_e32 v123, v0
	v_mov_b32_e32 v124, v0
	v_mov_b32_e32 v125, v0
	v_mov_b32_e32 v126, v0
	v_mov_b32_e32 v127, v0
	.p2align 6

.LBB0_1383:
	s_ashr_i32 s27, s26, 31
	v_cmp_lt_i64_e32 vcc, s[28:29], v[142:143]
	s_lshl_b64 s[28:29], s[26:27], 21
	s_add_u32 s28, s46, s28
	s_addc_u32 s29, s47, s29
	s_and_b64 s[30:31], vcc, exec
	s_cselect_b32 s27, s29, s35
	s_cselect_b32 s73, s28, s34
	s_ashr_i32 s21, s20, 31
	s_lshl_b64 s[30:31], s[20:21], 21
	s_add_u32 s30, s41, s30
	s_addc_u32 s31, s42, s31
	s_and_b64 s[38:39], vcc, exec
	s_cselect_b32 s21, s31, s37
	s_cselect_b32 s74, s30, s36
	s_add_u32 s34, s34, 0x100080
	s_addc_u32 s35, s35, 0
	s_add_u32 s75, s36, 0x100
	v_mov_b32_e32 v0, 0
	s_addc_u32 s76, s37, 0
	s_mov_b32 s77, -2
	v_mov_b32_e32 v1, v0
	v_mov_b32_e32 v2, v0
	v_mov_b32_e32 v3, v0
	v_mov_b32_e32 v4, v0
	v_mov_b32_e32 v5, v0
	v_mov_b32_e32 v6, v0
	v_mov_b32_e32 v7, v0
	v_mov_b32_e32 v8, v0
	v_mov_b32_e32 v9, v0
	v_mov_b32_e32 v10, v0
	v_mov_b32_e32 v11, v0
	v_mov_b32_e32 v12, v0
	v_mov_b32_e32 v13, v0
	v_mov_b32_e32 v14, v0
	v_mov_b32_e32 v15, v0
	v_mov_b32_e32 v24, v0
	v_mov_b32_e32 v25, v0
	v_mov_b32_e32 v26, v0
	v_mov_b32_e32 v27, v0
	v_mov_b32_e32 v28, v0
	v_mov_b32_e32 v29, v0
	v_mov_b32_e32 v30, v0
	v_mov_b32_e32 v31, v0
	v_mov_b32_e32 v40, v0
	v_mov_b32_e32 v41, v0
	v_mov_b32_e32 v42, v0
	v_mov_b32_e32 v43, v0
	v_mov_b32_e32 v44, v0
	v_mov_b32_e32 v45, v0
	v_mov_b32_e32 v46, v0
	v_mov_b32_e32 v47, v0
	v_mov_b32_e32 v16, v0
	v_mov_b32_e32 v17, v0
	v_mov_b32_e32 v18, v0
	v_mov_b32_e32 v19, v0
	v_mov_b32_e32 v20, v0
	v_mov_b32_e32 v21, v0
	v_mov_b32_e32 v22, v0
	v_mov_b32_e32 v23, v0
	v_mov_b32_e32 v32, v0
	v_mov_b32_e32 v33, v0
	v_mov_b32_e32 v34, v0
	v_mov_b32_e32 v35, v0
	v_mov_b32_e32 v36, v0
	v_mov_b32_e32 v37, v0
	v_mov_b32_e32 v38, v0
	v_mov_b32_e32 v39, v0
	v_mov_b32_e32 v48, v0
	v_mov_b32_e32 v49, v0
	v_mov_b32_e32 v50, v0
	v_mov_b32_e32 v51, v0
	v_mov_b32_e32 v52, v0
	v_mov_b32_e32 v53, v0
	v_mov_b32_e32 v54, v0
	v_mov_b32_e32 v55, v0
	v_mov_b32_e32 v56, v0
	v_mov_b32_e32 v57, v0
	v_mov_b32_e32 v58, v0
	v_mov_b32_e32 v59, v0
	v_mov_b32_e32 v60, v0
	v_mov_b32_e32 v61, v0
	v_mov_b32_e32 v62, v0
	v_mov_b32_e32 v63, v0
	v_mov_b32_e32 v64, v0
	v_mov_b32_e32 v65, v0
	v_mov_b32_e32 v66, v0
	v_mov_b32_e32 v67, v0
	v_mov_b32_e32 v68, v0
	v_mov_b32_e32 v69, v0
	v_mov_b32_e32 v70, v0
	v_mov_b32_e32 v71, v0
	v_mov_b32_e32 v72, v0
	v_mov_b32_e32 v73, v0
	v_mov_b32_e32 v74, v0
	v_mov_b32_e32 v75, v0
	v_mov_b32_e32 v76, v0
	v_mov_b32_e32 v77, v0
	v_mov_b32_e32 v78, v0
	v_mov_b32_e32 v79, v0
	v_mov_b32_e32 v88, v0
	v_mov_b32_e32 v89, v0
	v_mov_b32_e32 v90, v0
	v_mov_b32_e32 v91, v0
	v_mov_b32_e32 v92, v0
	v_mov_b32_e32 v93, v0
	v_mov_b32_e32 v94, v0
	v_mov_b32_e32 v95, v0
	v_mov_b32_e32 v104, v0
	v_mov_b32_e32 v105, v0
	v_mov_b32_e32 v106, v0
	v_mov_b32_e32 v107, v0
	v_mov_b32_e32 v108, v0
	v_mov_b32_e32 v109, v0
	v_mov_b32_e32 v110, v0
	v_mov_b32_e32 v111, v0
	v_mov_b32_e32 v80, v0
	v_mov_b32_e32 v81, v0
	v_mov_b32_e32 v82, v0
	v_mov_b32_e32 v83, v0
	v_mov_b32_e32 v84, v0
	v_mov_b32_e32 v85, v0
	v_mov_b32_e32 v86, v0
	v_mov_b32_e32 v87, v0
	v_mov_b32_e32 v96, v0
	v_mov_b32_e32 v97, v0
	v_mov_b32_e32 v98, v0
	v_mov_b32_e32 v99, v0
	v_mov_b32_e32 v100, v0
	v_mov_b32_e32 v101, v0
	v_mov_b32_e32 v102, v0
	v_mov_b32_e32 v103, v0
	v_mov_b32_e32 v112, v0
	v_mov_b32_e32 v113, v0
	v_mov_b32_e32 v114, v0
	v_mov_b32_e32 v115, v0
	v_mov_b32_e32 v116, v0
	v_mov_b32_e32 v117, v0
	v_mov_b32_e32 v118, v0
	v_mov_b32_e32 v119, v0
	v_mov_b32_e32 v120, v0
	v_mov_b32_e32 v121, v0
	v_mov_b32_e32 v122, v0
	v_mov_b32_e32 v123, v0
	v_mov_b32_e32 v124, v0
	v_mov_b32_e32 v125, v0
	v_mov_b32_e32 v126, v0
	v_mov_b32_e32 v127, v0
	.p2align 6
